# NA attention: 32 exec-masked serialized bias reads replaced by branch-free batched reads + v_cndmask; same numerics
# speedup vs baseline: 1.0323x; 1.0079x over previous
.LBB0_286:
	s_bitcmp1_b32 s36, 0
	s_cselect_b32 s12, 0x12000, 0
	s_add_i32 s17, s37, s12
	v_add3_u32 v0, s17, v146, v149
	ds_read_b128 v[18:21], v0
	ds_read_b128 v[22:25], v0 offset:32
	v_mov_b64_e32 v[94:95], v[78:79]
	v_mov_b64_e32 v[92:93], v[76:77]
	v_mov_b64_e32 v[90:91], v[74:75]
	s_waitcnt lgkmcnt(1)
	v_mfma_f32_32x32x16_bf16 v[2:17], v[18:21], v[96:99], v[64:79]
	ds_read_b128 v[18:21], v0 offset:64
	v_mov_b64_e32 v[88:89], v[72:73]
	v_mov_b64_e32 v[86:87], v[70:71]
	v_mov_b64_e32 v[84:85], v[68:69]
	v_mov_b64_e32 v[82:83], v[66:67]
	v_mov_b64_e32 v[80:81], v[64:65]
	v_mov_b32_e32 v1, 0xf149f2ca
	s_waitcnt lgkmcnt(1)
	v_mfma_f32_32x32x16_bf16 v[2:17], v[22:25], v[100:103], v[2:17]
	s_waitcnt lgkmcnt(0)
	v_mfma_f32_32x32x16_bf16 v[2:17], v[18:21], v[104:107], v[2:17]
	ds_read_b128 v[18:21], v0 offset:96
	s_waitcnt lgkmcnt(0)
	v_mfma_f32_32x32x16_bf16 v[2:17], v[18:21], v[108:111], v[2:17]
	ds_read_b128 v[18:21], v0 offset:4608
	s_waitcnt lgkmcnt(0)
	v_mfma_f32_32x32x16_bf16 v[80:95], v[18:21], v[96:99], v[80:95]
	ds_read_b128 v[18:21], v0 offset:4640
	s_waitcnt lgkmcnt(0)
	v_mfma_f32_32x32x16_bf16 v[80:95], v[18:21], v[100:103], v[80:95]
	ds_read_b128 v[18:21], v0 offset:4672
	s_waitcnt lgkmcnt(0)
	v_mfma_f32_32x32x16_bf16 v[80:95], v[18:21], v[104:107], v[80:95]
	ds_read_b128 v[18:21], v0 offset:4704
	v_mov_b32_e32 v0, 0xf149f2ca
	s_waitcnt lgkmcnt(0)
	v_mfma_f32_32x32x16_bf16 v[80:95], v[18:21], v[108:111], v[80:95]
	v_mov_b32_e32 v203, 0xf149f2ca
	v_add_u32_e32 v189, s16, v155
	ds_read_b32 v189, v189
	v_add_u32_e32 v190, s16, v156
	ds_read_b32 v190, v190
	v_add_u32_e32 v191, s16, v157
	ds_read_b32 v191, v191
	v_add_u32_e32 v192, s16, v158
	ds_read_b32 v192, v192
	v_add_u32_e32 v193, s16, v159
	ds_read_b32 v193, v193
	v_add_u32_e32 v194, s16, v160
	ds_read_b32 v194, v194
	v_add_u32_e32 v195, s16, v161
	ds_read_b32 v195, v195
	v_add_u32_e32 v196, s16, v162
	ds_read_b32 v196, v196
	v_add_u32_e32 v197, s16, v163
	ds_read_b32 v197, v197
	v_add_u32_e32 v198, s16, v164
	ds_read_b32 v198, v198
	v_add_u32_e32 v199, s16, v165
	ds_read_b32 v199, v199
	v_add_u32_e32 v202, s16, v166
	ds_read_b32 v202, v202
	s_waitcnt lgkmcnt(11)
	v_add_f32_e32 v189, v2, v189
	v_cndmask_b32_e64 v0, v203, v189, s[2:3]
	v_add_u32_e32 v189, s16, v167
	ds_read_b32 v189, v189
	s_waitcnt lgkmcnt(11)
	v_add_f32_e32 v190, v3, v190
	v_cndmask_b32_e64 v1, v203, v190, s[48:49]
	v_add_u32_e32 v190, s16, v168
	ds_read_b32 v190, v190
	s_waitcnt lgkmcnt(11)
	v_add_f32_e32 v191, v4, v191
	v_cndmask_b32_e64 v2, v203, v191, s[52:53]
	v_add_u32_e32 v191, s16, v169
	ds_read_b32 v191, v191
	s_waitcnt lgkmcnt(11)
	v_add_f32_e32 v192, v5, v192
	v_cndmask_b32_e64 v3, v203, v192, s[54:55]
	v_add_u32_e32 v192, s16, v170
	ds_read_b32 v192, v192
	s_waitcnt lgkmcnt(11)
	v_add_f32_e32 v193, v6, v193
	v_cndmask_b32_e64 v4, v203, v193, s[56:57]
	v_add_u32_e32 v193, s16, v171
	ds_read_b32 v193, v193
	s_waitcnt lgkmcnt(11)
	v_add_f32_e32 v194, v7, v194
	v_cndmask_b32_e64 v5, v203, v194, s[58:59]
	v_add_u32_e32 v194, s16, v172
	ds_read_b32 v194, v194
	s_waitcnt lgkmcnt(11)
	v_add_f32_e32 v195, v8, v195
	v_cndmask_b32_e64 v6, v203, v195, s[60:61]
	v_add_u32_e32 v195, s16, v173
	ds_read_b32 v195, v195
	s_waitcnt lgkmcnt(11)
	v_add_f32_e32 v196, v9, v196
	v_cndmask_b32_e64 v7, v203, v196, s[62:63]
	v_add_u32_e32 v196, s16, v174
	ds_read_b32 v196, v196
	s_waitcnt lgkmcnt(11)
	v_add_f32_e32 v197, v10, v197
	v_cndmask_b32_e64 v8, v203, v197, s[64:65]
	v_add_u32_e32 v197, s16, v175
	ds_read_b32 v197, v197
	s_waitcnt lgkmcnt(11)
	v_add_f32_e32 v198, v11, v198
	v_cndmask_b32_e64 v9, v203, v198, s[66:67]
	v_add_u32_e32 v198, s16, v176
	ds_read_b32 v198, v198
	s_waitcnt lgkmcnt(11)
	v_add_f32_e32 v199, v12, v199
	v_cndmask_b32_e64 v10, v203, v199, s[68:69]
	v_add_u32_e32 v199, s16, v177
	ds_read_b32 v199, v199
	s_waitcnt lgkmcnt(11)
	v_add_f32_e32 v202, v13, v202
	v_cndmask_b32_e64 v11, v203, v202, s[70:71]
	v_add_u32_e32 v202, s16, v178
	ds_read_b32 v202, v202
	s_waitcnt lgkmcnt(11)
	v_add_f32_e32 v189, v14, v189
	v_cndmask_b32_e64 v12, v203, v189, s[72:73]
	v_add_u32_e32 v189, s16, v179
	ds_read_b32 v189, v189
	s_waitcnt lgkmcnt(11)
	v_add_f32_e32 v190, v15, v190
	v_cndmask_b32_e64 v13, v203, v190, s[74:75]
	v_add_u32_e32 v190, s16, v180
	ds_read_b32 v190, v190
	s_waitcnt lgkmcnt(11)
	v_add_f32_e32 v191, v16, v191
	v_cndmask_b32_e64 v14, v203, v191, s[76:77]
	v_add_u32_e32 v191, s16, v181
	ds_read_b32 v191, v191
	s_waitcnt lgkmcnt(11)
	v_add_f32_e32 v192, v17, v192
	v_cndmask_b32_e64 v15, v203, v192, s[78:79]
	v_add_u32_e32 v192, s16, v182
	ds_read_b32 v192, v192
	s_waitcnt lgkmcnt(11)
	v_add_f32_e32 v193, v80, v193
	v_cndmask_b32_e64 v16, v203, v193, s[80:81]
	v_add_u32_e32 v193, s16, v183
	ds_read_b32 v193, v193
	s_waitcnt lgkmcnt(11)
	v_add_f32_e32 v194, v81, v194
	v_cndmask_b32_e64 v17, v203, v194, s[82:83]
	v_add_u32_e32 v194, s16, v184
	ds_read_b32 v194, v194
	s_waitcnt lgkmcnt(11)
	v_add_f32_e32 v195, v82, v195
	v_cndmask_b32_e64 v18, v203, v195, s[84:85]
	v_add_u32_e32 v195, s16, v185
	ds_read_b32 v195, v195
	s_waitcnt lgkmcnt(11)
	v_add_f32_e32 v196, v83, v196
	v_cndmask_b32_e64 v19, v203, v196, s[86:87]
	v_add_u32_e32 v196, s16, v186
	ds_read_b32 v196, v196
	s_waitcnt lgkmcnt(11)
	v_add_f32_e32 v197, v84, v197
	v_cndmask_b32_e64 v20, v203, v197, s[88:89]
	s_waitcnt lgkmcnt(10)
	v_add_f32_e32 v198, v85, v198
	v_cndmask_b32_e64 v21, v203, v198, s[90:91]
	s_waitcnt lgkmcnt(9)
	v_add_f32_e32 v199, v86, v199
	v_cndmask_b32_e64 v22, v203, v199, s[92:93]
	s_waitcnt lgkmcnt(8)
	v_add_f32_e32 v202, v87, v202
	v_cndmask_b32_e64 v23, v203, v202, s[94:95]
	s_waitcnt lgkmcnt(7)
	v_add_f32_e32 v189, v88, v189
	v_cndmask_b32_e64 v24, v203, v189, s[96:97]
	s_waitcnt lgkmcnt(6)
	v_add_f32_e32 v190, v89, v190
	v_cndmask_b32_e64 v25, v203, v190, s[40:41]
	s_waitcnt lgkmcnt(5)
	v_add_f32_e32 v191, v90, v191
	v_cndmask_b32_e64 v26, v203, v191, s[38:39]
	s_waitcnt lgkmcnt(4)
	v_add_f32_e32 v192, v91, v192
	v_cndmask_b32_e64 v27, v203, v192, s[44:45]
	s_waitcnt lgkmcnt(3)
	v_add_f32_e32 v193, v92, v193
	v_cndmask_b32_e64 v28, v203, v193, s[4:5]
	s_waitcnt lgkmcnt(2)
	v_add_f32_e32 v194, v93, v194
	v_cndmask_b32_e64 v29, v203, v194, s[42:43]
	s_waitcnt lgkmcnt(1)
	v_add_f32_e32 v195, v94, v195
	v_cndmask_b32_e64 v30, v203, v195, s[50:51]
	s_waitcnt lgkmcnt(0)
	v_add_f32_e32 v196, v95, v196
	v_cndmask_b32_e64 v31, v203, v196, s[6:7]
.LBB0_348:
	s_mov_b64 vcc, exec
	s_cmp_lg_u32 s16, 0
	s_cbranch_scc0 .LBB0_355
